# adds mLSTM-out exp-block LDS preload, pipelined qk MFMA chain with counted lgkmcnt, adaLN GEMV unrolled x2 (16 loads in flight)
# speedup vs baseline: 1.0053x; 1.0053x over previous
.LBB0_13:
	v_lshl_add_u64 v[24:25], v[6:7], 0, s[12:13]
	v_add_co_u32_e32 v26, vcc, s14, v24
	global_load_dwordx2 v[64:65], v[24:25], off
	s_nop 0
	v_addc_co_u32_e32 v27, vcc, 0, v25, vcc
	v_add_co_u32_e32 v28, vcc, s15, v24
	v_mov_b32_e32 v23, s9
	s_nop 0
	v_addc_co_u32_e32 v29, vcc, 0, v25, vcc
	v_add_co_u32_e32 v30, vcc, s16, v24
	s_add_u32 s12, s12, 0x60000
	s_nop 0
	v_addc_co_u32_e32 v31, vcc, 0, v25, vcc
	v_add_co_u32_e32 v32, vcc, s17, v24
	s_addc_u32 s13, s13, 0
	s_nop 0
	v_addc_co_u32_e32 v33, vcc, 0, v25, vcc
	v_add_co_u32_e32 v34, vcc, s18, v24
	s_add_i32 s9, s9, 32
	s_nop 0
	v_addc_co_u32_e32 v35, vcc, 0, v25, vcc
	v_add_co_u32_e32 v36, vcc, s19, v24
	s_cmp_eq_u32 s12, 0x300000
	s_nop 0
	v_addc_co_u32_e32 v37, vcc, 0, v25, vcc
	v_add_co_u32_e32 v24, vcc, s20, v24
	s_nop 1
	v_addc_co_u32_e32 v25, vcc, 0, v25, vcc
	global_load_dwordx2 v[66:67], v[26:27], off
	global_load_dwordx2 v[68:69], v[28:29], off
	global_load_dwordx2 v[70:71], v[30:31], off
	global_load_dwordx2 v[72:73], v[32:33], off
	global_load_dwordx2 v[74:75], v[34:35], off
	global_load_dwordx2 v[76:77], v[36:37], off
	global_load_dwordx2 v[78:79], v[24:25], off
	v_lshl_add_u64 v[100:101], v[6:7], 0, s[12:13]
	v_add_co_u32_e32 v102, vcc, s14, v100
	global_load_dwordx2 v[160:161], v[100:101], off
	s_nop 0
	v_addc_co_u32_e32 v103, vcc, 0, v101, vcc
	v_add_co_u32_e32 v104, vcc, s15, v100
	v_mov_b32_e32 v142, s9
	s_nop 0
	v_addc_co_u32_e32 v105, vcc, 0, v101, vcc
	v_add_co_u32_e32 v106, vcc, s16, v100
	s_add_u32 s12, s12, 0x60000
	s_nop 0
	v_addc_co_u32_e32 v107, vcc, 0, v101, vcc
	v_add_co_u32_e32 v108, vcc, s17, v100
	s_addc_u32 s13, s13, 0
	s_nop 0
	v_addc_co_u32_e32 v109, vcc, 0, v101, vcc
	v_add_co_u32_e32 v110, vcc, s18, v100
	s_add_i32 s9, s9, 32
	s_nop 0
	v_addc_co_u32_e32 v111, vcc, 0, v101, vcc
	v_add_co_u32_e32 v112, vcc, s19, v100
	s_cmp_eq_u32 s12, 0x300000
	s_nop 0
	v_addc_co_u32_e32 v113, vcc, 0, v101, vcc
	v_add_co_u32_e32 v100, vcc, s20, v100
	s_nop 1
	v_addc_co_u32_e32 v101, vcc, 0, v101, vcc
	global_load_dwordx2 v[162:163], v[102:103], off
	global_load_dwordx2 v[164:165], v[104:105], off
	global_load_dwordx2 v[166:167], v[106:107], off
	global_load_dwordx2 v[168:169], v[108:109], off
	global_load_dwordx2 v[170:171], v[110:111], off
	global_load_dwordx2 v[172:173], v[112:113], off
	global_load_dwordx2 v[174:175], v[100:101], off
	ds_read_b128 v[24:27], v23
	ds_read_b128 v[28:31], v23 offset:16
	ds_read_b128 v[32:35], v23 offset:256
	ds_read_b128 v[36:39], v23 offset:272
	ds_read_b128 v[40:43], v23 offset:512
	ds_read_b128 v[44:47], v23 offset:528
	ds_read_b128 v[48:51], v23 offset:768
	ds_read_b128 v[52:55], v23 offset:784
	ds_read_b128 v[56:59], v23 offset:1024
	ds_read_b128 v[60:63], v23 offset:1040
	s_waitcnt lgkmcnt(9)
	v_mov_b32_e32 v80, v27
	s_waitcnt lgkmcnt(7)
	v_mov_b32_e32 v82, v35
	s_waitcnt lgkmcnt(5)
	v_mov_b32_e32 v84, v43
	s_waitcnt lgkmcnt(3)
	v_mov_b32_e32 v86, v51
	s_waitcnt lgkmcnt(1)
	v_mov_b32_e32 v88, v59
	v_mov_b32_e32 v90, v31
	v_mov_b32_e32 v92, v39
	v_mov_b32_e32 v94, v47
	v_mov_b32_e32 v96, v55
	s_waitcnt lgkmcnt(0)
	v_mov_b32_e32 v98, v63
	s_waitcnt vmcnt(15)
	v_pk_fma_f32 v[14:15], v[64:65], v[24:25], v[14:15] op_sel_hi:[1,0,1]
	v_pk_fma_f32 v[16:17], v[64:65], v[32:33], v[16:17] op_sel_hi:[1,0,1]
	v_pk_fma_f32 v[12:13], v[64:65], v[40:41], v[12:13] op_sel_hi:[1,0,1]
	v_pk_fma_f32 v[10:11], v[64:65], v[48:49], v[10:11] op_sel_hi:[1,0,1]
	v_pk_fma_f32 v[8:9], v[64:65], v[56:57], v[8:9] op_sel_hi:[1,0,1]
	s_waitcnt vmcnt(14)
	v_pk_fma_f32 v[14:15], v[66:67], v[24:25], v[14:15] op_sel:[0,1,0]
	v_pk_fma_f32 v[16:17], v[66:67], v[32:33], v[16:17] op_sel:[0,1,0]
	v_pk_fma_f32 v[12:13], v[66:67], v[40:41], v[12:13] op_sel:[0,1,0]
	v_pk_fma_f32 v[10:11], v[66:67], v[48:49], v[10:11] op_sel:[0,1,0]
	v_pk_fma_f32 v[8:9], v[66:67], v[56:57], v[8:9] op_sel:[0,1,0]
	s_waitcnt vmcnt(13)
	v_pk_fma_f32 v[14:15], v[68:69], v[26:27], v[14:15] op_sel_hi:[1,0,1]
	v_pk_fma_f32 v[16:17], v[68:69], v[34:35], v[16:17] op_sel_hi:[1,0,1]
	v_pk_fma_f32 v[12:13], v[68:69], v[42:43], v[12:13] op_sel_hi:[1,0,1]
	v_pk_fma_f32 v[10:11], v[68:69], v[50:51], v[10:11] op_sel_hi:[1,0,1]
	v_pk_fma_f32 v[8:9], v[68:69], v[58:59], v[8:9] op_sel_hi:[1,0,1]
	s_waitcnt vmcnt(12)
	v_pk_fma_f32 v[14:15], v[70:71], v[80:81], v[14:15] op_sel_hi:[1,0,1]
	v_pk_fma_f32 v[16:17], v[70:71], v[82:83], v[16:17] op_sel_hi:[1,0,1]
	v_pk_fma_f32 v[12:13], v[70:71], v[84:85], v[12:13] op_sel_hi:[1,0,1]
	v_pk_fma_f32 v[10:11], v[70:71], v[86:87], v[10:11] op_sel_hi:[1,0,1]
	v_pk_fma_f32 v[8:9], v[70:71], v[88:89], v[8:9] op_sel_hi:[1,0,1]
	s_waitcnt vmcnt(11)
	v_pk_fma_f32 v[14:15], v[72:73], v[28:29], v[14:15] op_sel_hi:[1,0,1]
	v_pk_fma_f32 v[16:17], v[72:73], v[36:37], v[16:17] op_sel_hi:[1,0,1]
	v_pk_fma_f32 v[12:13], v[72:73], v[44:45], v[12:13] op_sel_hi:[1,0,1]
	v_pk_fma_f32 v[10:11], v[72:73], v[52:53], v[10:11] op_sel_hi:[1,0,1]
	v_pk_fma_f32 v[8:9], v[72:73], v[60:61], v[8:9] op_sel_hi:[1,0,1]
	s_waitcnt vmcnt(10)
	v_pk_fma_f32 v[14:15], v[74:75], v[28:29], v[14:15] op_sel:[0,1,0]
	v_pk_fma_f32 v[16:17], v[74:75], v[36:37], v[16:17] op_sel:[0,1,0]
	v_pk_fma_f32 v[12:13], v[74:75], v[44:45], v[12:13] op_sel:[0,1,0]
	v_pk_fma_f32 v[10:11], v[74:75], v[52:53], v[10:11] op_sel:[0,1,0]
	v_pk_fma_f32 v[8:9], v[74:75], v[60:61], v[8:9] op_sel:[0,1,0]
	s_waitcnt vmcnt(9)
	v_pk_fma_f32 v[14:15], v[76:77], v[30:31], v[14:15] op_sel_hi:[1,0,1]
	v_pk_fma_f32 v[16:17], v[76:77], v[38:39], v[16:17] op_sel_hi:[1,0,1]
	v_pk_fma_f32 v[12:13], v[76:77], v[46:47], v[12:13] op_sel_hi:[1,0,1]
	v_pk_fma_f32 v[10:11], v[76:77], v[54:55], v[10:11] op_sel_hi:[1,0,1]
	v_pk_fma_f32 v[8:9], v[76:77], v[62:63], v[8:9] op_sel_hi:[1,0,1]
	s_waitcnt vmcnt(8)
	v_pk_fma_f32 v[14:15], v[78:79], v[90:91], v[14:15] op_sel_hi:[1,0,1]
	v_pk_fma_f32 v[16:17], v[78:79], v[92:93], v[16:17] op_sel_hi:[1,0,1]
	v_pk_fma_f32 v[12:13], v[78:79], v[94:95], v[12:13] op_sel_hi:[1,0,1]
	v_pk_fma_f32 v[10:11], v[78:79], v[96:97], v[10:11] op_sel_hi:[1,0,1]
	v_pk_fma_f32 v[8:9], v[78:79], v[98:99], v[8:9] op_sel_hi:[1,0,1]
	ds_read_b128 v[100:103], v142
	ds_read_b128 v[104:107], v142 offset:16
	ds_read_b128 v[108:111], v142 offset:256
	ds_read_b128 v[112:115], v142 offset:272
	ds_read_b128 v[116:119], v142 offset:512
	ds_read_b128 v[120:123], v142 offset:528
	ds_read_b128 v[124:127], v142 offset:768
	ds_read_b128 v[128:131], v142 offset:784
	ds_read_b128 v[132:135], v142 offset:1024
	ds_read_b128 v[136:139], v142 offset:1040
	s_waitcnt lgkmcnt(9)
	v_mov_b32_e32 v200, v103
	s_waitcnt lgkmcnt(7)
	v_mov_b32_e32 v202, v111
	s_waitcnt lgkmcnt(5)
	v_mov_b32_e32 v204, v119
	s_waitcnt lgkmcnt(3)
	v_mov_b32_e32 v206, v127
	s_waitcnt lgkmcnt(1)
	v_mov_b32_e32 v208, v135
	v_mov_b32_e32 v210, v107
	v_mov_b32_e32 v212, v115
	v_mov_b32_e32 v214, v123
	v_mov_b32_e32 v216, v131
	s_waitcnt lgkmcnt(0)
	v_mov_b32_e32 v218, v139
	s_waitcnt vmcnt(7)
	v_pk_fma_f32 v[14:15], v[160:161], v[100:101], v[14:15] op_sel_hi:[1,0,1]
	v_pk_fma_f32 v[16:17], v[160:161], v[108:109], v[16:17] op_sel_hi:[1,0,1]
	v_pk_fma_f32 v[12:13], v[160:161], v[116:117], v[12:13] op_sel_hi:[1,0,1]
	v_pk_fma_f32 v[10:11], v[160:161], v[124:125], v[10:11] op_sel_hi:[1,0,1]
	v_pk_fma_f32 v[8:9], v[160:161], v[132:133], v[8:9] op_sel_hi:[1,0,1]
	s_waitcnt vmcnt(6)
	v_pk_fma_f32 v[14:15], v[162:163], v[100:101], v[14:15] op_sel:[0,1,0]
	v_pk_fma_f32 v[16:17], v[162:163], v[108:109], v[16:17] op_sel:[0,1,0]
	v_pk_fma_f32 v[12:13], v[162:163], v[116:117], v[12:13] op_sel:[0,1,0]
	v_pk_fma_f32 v[10:11], v[162:163], v[124:125], v[10:11] op_sel:[0,1,0]
	v_pk_fma_f32 v[8:9], v[162:163], v[132:133], v[8:9] op_sel:[0,1,0]
	s_waitcnt vmcnt(5)
	v_pk_fma_f32 v[14:15], v[164:165], v[102:103], v[14:15] op_sel_hi:[1,0,1]
	v_pk_fma_f32 v[16:17], v[164:165], v[110:111], v[16:17] op_sel_hi:[1,0,1]
	v_pk_fma_f32 v[12:13], v[164:165], v[118:119], v[12:13] op_sel_hi:[1,0,1]
	v_pk_fma_f32 v[10:11], v[164:165], v[126:127], v[10:11] op_sel_hi:[1,0,1]
	v_pk_fma_f32 v[8:9], v[164:165], v[134:135], v[8:9] op_sel_hi:[1,0,1]
	s_waitcnt vmcnt(4)
	v_pk_fma_f32 v[14:15], v[166:167], v[200:201], v[14:15] op_sel_hi:[1,0,1]
	v_pk_fma_f32 v[16:17], v[166:167], v[202:203], v[16:17] op_sel_hi:[1,0,1]
	v_pk_fma_f32 v[12:13], v[166:167], v[204:205], v[12:13] op_sel_hi:[1,0,1]
	v_pk_fma_f32 v[10:11], v[166:167], v[206:207], v[10:11] op_sel_hi:[1,0,1]
	v_pk_fma_f32 v[8:9], v[166:167], v[208:209], v[8:9] op_sel_hi:[1,0,1]
	s_waitcnt vmcnt(3)
	v_pk_fma_f32 v[14:15], v[168:169], v[104:105], v[14:15] op_sel_hi:[1,0,1]
	v_pk_fma_f32 v[16:17], v[168:169], v[112:113], v[16:17] op_sel_hi:[1,0,1]
	v_pk_fma_f32 v[12:13], v[168:169], v[120:121], v[12:13] op_sel_hi:[1,0,1]
	v_pk_fma_f32 v[10:11], v[168:169], v[128:129], v[10:11] op_sel_hi:[1,0,1]
	v_pk_fma_f32 v[8:9], v[168:169], v[136:137], v[8:9] op_sel_hi:[1,0,1]
	s_waitcnt vmcnt(2)
	v_pk_fma_f32 v[14:15], v[170:171], v[104:105], v[14:15] op_sel:[0,1,0]
	v_pk_fma_f32 v[16:17], v[170:171], v[112:113], v[16:17] op_sel:[0,1,0]
	v_pk_fma_f32 v[12:13], v[170:171], v[120:121], v[12:13] op_sel:[0,1,0]
	v_pk_fma_f32 v[10:11], v[170:171], v[128:129], v[10:11] op_sel:[0,1,0]
	v_pk_fma_f32 v[8:9], v[170:171], v[136:137], v[8:9] op_sel:[0,1,0]
	s_waitcnt vmcnt(1)
	v_pk_fma_f32 v[14:15], v[172:173], v[106:107], v[14:15] op_sel_hi:[1,0,1]
	v_pk_fma_f32 v[16:17], v[172:173], v[114:115], v[16:17] op_sel_hi:[1,0,1]
	v_pk_fma_f32 v[12:13], v[172:173], v[122:123], v[12:13] op_sel_hi:[1,0,1]
	v_pk_fma_f32 v[10:11], v[172:173], v[130:131], v[10:11] op_sel_hi:[1,0,1]
	v_pk_fma_f32 v[8:9], v[172:173], v[138:139], v[8:9] op_sel_hi:[1,0,1]
	s_waitcnt vmcnt(0)
	v_pk_fma_f32 v[14:15], v[174:175], v[210:211], v[14:15] op_sel_hi:[1,0,1]
	v_pk_fma_f32 v[16:17], v[174:175], v[212:213], v[16:17] op_sel_hi:[1,0,1]
	v_pk_fma_f32 v[12:13], v[174:175], v[214:215], v[12:13] op_sel_hi:[1,0,1]
	v_pk_fma_f32 v[10:11], v[174:175], v[216:217], v[10:11] op_sel_hi:[1,0,1]
	v_pk_fma_f32 v[8:9], v[174:175], v[218:219], v[8:9] op_sel_hi:[1,0,1]
	s_cbranch_scc0 .LBB0_13
	s_ashr_i32 s9, s8, 31
	s_lshl_b64 s[8:9], s[8:9], 1
	s_add_u32 s8, s8, s10
	s_addc_u32 s9, s9, s11
	s_mul_i32 s9, s9, 0x3c000
	s_mul_hi_u32 s10, s8, 0x3c000
	s_add_i32 s10, s10, s9
	s_mul_i32 s8, s8, 0x3c000
	s_add_u32 s8, s2, s8
	s_addc_u32 s9, s3, s10
	v_lshl_add_u64 v[4:5], v[4:5], 2, s[8:9]
	v_add_co_u32_e32 v6, vcc, s14, v4
	global_store_dwordx2 v[4:5], v[14:15], off
	s_nop 0
	v_addc_co_u32_e32 v7, vcc, 0, v5, vcc
	global_store_dwordx2 v[6:7], v[16:17], off
	v_add_co_u32_e32 v6, vcc, 0x18000, v4
	s_add_i32 s21, s21, s86
	s_nop 0
	v_addc_co_u32_e32 v7, vcc, 0, v5, vcc
	global_store_dwordx2 v[6:7], v[12:13], off
	v_add_co_u32_e32 v6, vcc, 0x24000, v4
	s_cmpk_gt_i32 s21, 0x2ff
	s_nop 0
	v_addc_co_u32_e32 v7, vcc, 0, v5, vcc
	v_add_co_u32_e32 v4, vcc, 0x30000, v4
	global_store_dwordx2 v[6:7], v[10:11], off
	s_nop 0
	v_addc_co_u32_e32 v5, vcc, 0, v5, vcc
	global_store_dwordx2 v[4:5], v[8:9], off
	s_cbranch_scc0 .LBB0_8

.LBB0_2210:
	v_add_u32_e32 v60, v49, v104
	ds_read_b128 v[32:35], v60
	ds_read_b128 v[36:39], v105
	ds_read_b128 v[218:221], v60 offset:32
	ds_read_b128 v[222:225], v105 offset:32
	ds_read_b128 v[226:229], v60 offset:64
	ds_read_b128 v[230:233], v105 offset:64
	ds_read_b128 v[234:237], v60 offset:96
	ds_read_b128 v[238:241], v105 offset:96
	s_waitcnt lgkmcnt(6)
	v_mfma_f32_32x32x16_bf16 v[32:47], v[32:35], v[36:39], 0
	ds_read_b128 v[242:245], v60 offset:128
	ds_read_b128 v[246:249], v105 offset:128
	s_waitcnt lgkmcnt(6)
	v_mfma_f32_32x32x16_bf16 v[32:47], v[218:221], v[222:225], v[32:47]
	ds_read_b128 v[218:221], v60 offset:160
	ds_read_b128 v[222:225], v105 offset:160
	s_waitcnt lgkmcnt(6)
	v_mfma_f32_32x32x16_bf16 v[32:47], v[226:229], v[230:233], v[32:47]
	ds_read_b128 v[226:229], v60 offset:192
	ds_read_b128 v[230:233], v105 offset:192
	s_waitcnt lgkmcnt(6)
	v_mfma_f32_32x32x16_bf16 v[32:47], v[234:237], v[238:241], v[32:47]
	ds_read_b128 v[234:237], v60 offset:224
	ds_read_b128 v[238:241], v105 offset:224
	s_waitcnt lgkmcnt(6)
	v_mfma_f32_32x32x16_bf16 v[32:47], v[242:245], v[246:249], v[32:47]
	s_waitcnt lgkmcnt(4)
	v_mfma_f32_32x32x16_bf16 v[32:47], v[218:221], v[222:225], v[32:47]
	s_waitcnt lgkmcnt(2)
	v_mfma_f32_32x32x16_bf16 v[32:47], v[226:229], v[230:233], v[32:47]
	s_waitcnt lgkmcnt(0)
	v_mfma_f32_32x32x16_bf16 v[32:47], v[234:237], v[238:241], v[32:47]
	v_add_u32_e32 v55, s23, v107
	v_cmp_le_u32_e32 vcc, v55, v103
	v_add_u32_e32 v54, s22, v104
	v_add_u32_e32 v216, 0x22600, v54
	ds_read_b32 v200, v216
	ds_read_b32 v201, v216 offset:4
	ds_read_b32 v202, v216 offset:8
	ds_read_b32 v203, v216 offset:12
	ds_read_b32 v204, v216 offset:32
	ds_read_b32 v205, v216 offset:36
	ds_read_b32 v206, v216 offset:40
	ds_read_b32 v207, v216 offset:44
	ds_read_b32 v208, v216 offset:64
	ds_read_b32 v209, v216 offset:68
	ds_read_b32 v210, v216 offset:72
	ds_read_b32 v211, v216 offset:76
	s_waitcnt lgkmcnt(8)
	ds_read_b32 v212, v216 offset:96
	ds_read_b32 v213, v216 offset:100
	ds_read_b32 v214, v216 offset:104
	ds_read_b32 v215, v216 offset:108
	s_waitcnt lgkmcnt(0)
	v_mov_b32_e32 v52, 0
	s_and_saveexec_b64 s[20:21], vcc
	s_cbranch_execz .LBB0_2212
	v_mov_b32_e32 v52, v200
	v_sub_f32_e32 v52, v52, v48
	v_mul_f32_e32 v53, 0x3fb8aa3b, v52
	v_fma_f32 v56, v52, s97, -v53
	v_rndne_f32_e32 v57, v53
	v_fmac_f32_e32 v56, 0x32a5705f, v52
	v_sub_f32_e32 v53, v53, v57
	v_add_f32_e32 v53, v53, v56
	v_cvt_i32_f32_e32 v57, v57
	v_exp_f32_e32 v53, v53
	v_cmp_ngt_f32_e32 vcc, s24, v52
	v_ldexp_f32 v53, v53, v57
	s_nop 0
	v_cndmask_b32_e32 v53, 0, v53, vcc
	v_cmp_nlt_f32_e32 vcc, s25, v52
	s_nop 1
	v_cndmask_b32_e32 v52, v188, v53, vcc
	v_mul_f32_e32 v52, v32, v52
.LBB0_2212:
	s_or_b64 exec, exec, s[20:21]
	v_cmp_lt_u32_e32 vcc, v55, v103
	s_nop 3
	v_mov_b32_e32 v32, 0
	v_mov_b32_e32 v53, 0
	s_and_saveexec_b64 s[20:21], vcc
	s_cbranch_execz .LBB0_2214
	v_mov_b32_e32 v53, v201
	v_sub_f32_e32 v53, v53, v48
	v_mul_f32_e32 v56, 0x3fb8aa3b, v53
	v_fma_f32 v57, v53, s97, -v56
	v_rndne_f32_e32 v58, v56
	v_fmac_f32_e32 v57, 0x32a5705f, v53
	v_sub_f32_e32 v56, v56, v58
	v_add_f32_e32 v56, v56, v57
	v_cvt_i32_f32_e32 v58, v58
	v_exp_f32_e32 v56, v56
	v_cmp_ngt_f32_e32 vcc, s24, v53
	v_ldexp_f32 v56, v56, v58
	s_nop 0
	v_cndmask_b32_e32 v56, 0, v56, vcc
	v_cmp_nlt_f32_e32 vcc, s25, v53
	s_nop 1
	v_cndmask_b32_e32 v53, v188, v56, vcc
	v_mul_f32_e32 v53, v33, v53
.LBB0_2214:
	s_or_b64 exec, exec, s[20:21]
	v_add_u32_e32 v33, 2, v55
	v_cmp_le_u32_e32 vcc, v33, v103
	s_and_saveexec_b64 s[20:21], vcc
	s_cbranch_execz .LBB0_2216
	v_mov_b32_e32 v32, v202
	v_sub_f32_e32 v32, v32, v48
	v_mul_f32_e32 v33, 0x3fb8aa3b, v32
	v_fma_f32 v56, v32, s97, -v33
	v_rndne_f32_e32 v57, v33
	v_fmac_f32_e32 v56, 0x32a5705f, v32
	v_sub_f32_e32 v33, v33, v57
	v_add_f32_e32 v33, v33, v56
	v_cvt_i32_f32_e32 v57, v57
	v_exp_f32_e32 v33, v33
	v_cmp_ngt_f32_e32 vcc, s24, v32
	v_ldexp_f32 v33, v33, v57
	s_nop 0
	v_cndmask_b32_e32 v33, 0, v33, vcc
	v_cmp_nlt_f32_e32 vcc, s25, v32
	s_nop 1
	v_cndmask_b32_e32 v32, v188, v33, vcc
	v_mul_f32_e32 v32, v34, v32
.LBB0_2216:
	s_or_b64 exec, exec, s[20:21]
	v_add_u32_e32 v33, 3, v55
	v_cmp_le_u32_e32 vcc, v33, v103
	v_mov_b32_e32 v33, 0
	v_mov_b32_e32 v34, 0
	s_and_saveexec_b64 s[20:21], vcc
	s_cbranch_execz .LBB0_2218
	v_mov_b32_e32 v34, v203
	v_sub_f32_e32 v34, v34, v48
	v_mul_f32_e32 v56, 0x3fb8aa3b, v34
	v_fma_f32 v57, v34, s97, -v56
	v_rndne_f32_e32 v58, v56
	v_fmac_f32_e32 v57, 0x32a5705f, v34
	v_sub_f32_e32 v56, v56, v58
	v_add_f32_e32 v56, v56, v57
	v_cvt_i32_f32_e32 v58, v58
	v_exp_f32_e32 v56, v56
	v_cmp_ngt_f32_e32 vcc, s24, v34
	v_ldexp_f32 v56, v56, v58
	s_nop 0
	v_cndmask_b32_e32 v56, 0, v56, vcc
	v_cmp_nlt_f32_e32 vcc, s25, v34
	s_nop 1
	v_cndmask_b32_e32 v34, v188, v56, vcc
	v_mul_f32_e32 v34, v35, v34
.LBB0_2218:
	s_or_b64 exec, exec, s[20:21]
	v_add_u32_e32 v35, 8, v55
	v_cmp_le_u32_e32 vcc, v35, v103
	s_and_saveexec_b64 s[20:21], vcc
	s_cbranch_execz .LBB0_2220
	v_mov_b32_e32 v33, v204
	v_sub_f32_e32 v33, v33, v48
	v_mul_f32_e32 v35, 0x3fb8aa3b, v33
	v_fma_f32 v56, v33, s97, -v35
	v_rndne_f32_e32 v57, v35
	v_fmac_f32_e32 v56, 0x32a5705f, v33
	v_sub_f32_e32 v35, v35, v57
	v_add_f32_e32 v35, v35, v56
	v_cvt_i32_f32_e32 v57, v57
	v_exp_f32_e32 v35, v35
	v_cmp_ngt_f32_e32 vcc, s24, v33
	v_ldexp_f32 v35, v35, v57
	s_nop 0
	v_cndmask_b32_e32 v35, 0, v35, vcc
	v_cmp_nlt_f32_e32 vcc, s25, v33
	s_nop 1
	v_cndmask_b32_e32 v33, v188, v35, vcc
	v_mul_f32_e32 v33, v36, v33
.LBB0_2220:
	s_or_b64 exec, exec, s[20:21]
	v_add_u32_e32 v35, 9, v55
	v_cmp_le_u32_e32 vcc, v35, v103
	v_mov_b32_e32 v35, 0
	v_mov_b32_e32 v36, 0
	s_and_saveexec_b64 s[20:21], vcc
	s_cbranch_execz .LBB0_2222
	v_mov_b32_e32 v36, v205
	v_sub_f32_e32 v36, v36, v48
	v_mul_f32_e32 v56, 0x3fb8aa3b, v36
	v_fma_f32 v57, v36, s97, -v56
	v_rndne_f32_e32 v58, v56
	v_fmac_f32_e32 v57, 0x32a5705f, v36
	v_sub_f32_e32 v56, v56, v58
	v_add_f32_e32 v56, v56, v57
	v_cvt_i32_f32_e32 v58, v58
	v_exp_f32_e32 v56, v56
	v_cmp_ngt_f32_e32 vcc, s24, v36
	v_ldexp_f32 v56, v56, v58
	s_nop 0
	v_cndmask_b32_e32 v56, 0, v56, vcc
	v_cmp_nlt_f32_e32 vcc, s25, v36
	s_nop 1
	v_cndmask_b32_e32 v36, v188, v56, vcc
	v_mul_f32_e32 v36, v37, v36
.LBB0_2222:
	s_or_b64 exec, exec, s[20:21]
	v_add_u32_e32 v37, 10, v55
	v_cmp_le_u32_e32 vcc, v37, v103
	s_and_saveexec_b64 s[20:21], vcc
	s_cbranch_execz .LBB0_2224
	v_mov_b32_e32 v35, v206
	v_sub_f32_e32 v35, v35, v48
	v_mul_f32_e32 v37, 0x3fb8aa3b, v35
	v_fma_f32 v56, v35, s97, -v37
	v_rndne_f32_e32 v57, v37
	v_fmac_f32_e32 v56, 0x32a5705f, v35
	v_sub_f32_e32 v37, v37, v57
	v_add_f32_e32 v37, v37, v56
	v_cvt_i32_f32_e32 v57, v57
	v_exp_f32_e32 v37, v37
	v_cmp_ngt_f32_e32 vcc, s24, v35
	v_ldexp_f32 v37, v37, v57
	s_nop 0
	v_cndmask_b32_e32 v37, 0, v37, vcc
	v_cmp_nlt_f32_e32 vcc, s25, v35
	s_nop 1
	v_cndmask_b32_e32 v35, v188, v37, vcc
	v_mul_f32_e32 v35, v38, v35
.LBB0_2224:
	s_or_b64 exec, exec, s[20:21]
	v_add_u32_e32 v37, 11, v55
	v_cmp_le_u32_e32 vcc, v37, v103
	v_mov_b32_e32 v37, 0
	v_mov_b32_e32 v38, 0
	s_and_saveexec_b64 s[20:21], vcc
	s_cbranch_execz .LBB0_2226
	v_mov_b32_e32 v38, v207
	v_sub_f32_e32 v38, v38, v48
	v_mul_f32_e32 v56, 0x3fb8aa3b, v38
	v_fma_f32 v57, v38, s97, -v56
	v_rndne_f32_e32 v58, v56
	v_fmac_f32_e32 v57, 0x32a5705f, v38
	v_sub_f32_e32 v56, v56, v58
	v_add_f32_e32 v56, v56, v57
	v_cvt_i32_f32_e32 v58, v58
	v_exp_f32_e32 v56, v56
	v_cmp_ngt_f32_e32 vcc, s24, v38
	v_ldexp_f32 v56, v56, v58
	s_nop 0
	v_cndmask_b32_e32 v56, 0, v56, vcc
	v_cmp_nlt_f32_e32 vcc, s25, v38
	s_nop 1
	v_cndmask_b32_e32 v38, v188, v56, vcc
	v_mul_f32_e32 v38, v39, v38
.LBB0_2226:
	s_or_b64 exec, exec, s[20:21]
	v_add_u32_e32 v39, 16, v55
	v_cmp_le_u32_e32 vcc, v39, v103
	s_and_saveexec_b64 s[20:21], vcc
	s_cbranch_execz .LBB0_2228
	v_mov_b32_e32 v37, v208
	v_sub_f32_e32 v37, v37, v48
	v_mul_f32_e32 v39, 0x3fb8aa3b, v37
	v_fma_f32 v56, v37, s97, -v39
	v_rndne_f32_e32 v57, v39
	v_fmac_f32_e32 v56, 0x32a5705f, v37
	v_sub_f32_e32 v39, v39, v57
	v_add_f32_e32 v39, v39, v56
	v_cvt_i32_f32_e32 v57, v57
	v_exp_f32_e32 v39, v39
	v_cmp_ngt_f32_e32 vcc, s24, v37
	v_ldexp_f32 v39, v39, v57
	s_nop 0
	v_cndmask_b32_e32 v39, 0, v39, vcc
	v_cmp_nlt_f32_e32 vcc, s25, v37
	s_nop 1
	v_cndmask_b32_e32 v37, v188, v39, vcc
	v_mul_f32_e32 v37, v40, v37
.LBB0_2228:
	s_or_b64 exec, exec, s[20:21]
	v_add_u32_e32 v39, 17, v55
	v_cmp_le_u32_e32 vcc, v39, v103
	v_mov_b32_e32 v39, 0
	v_mov_b32_e32 v40, 0
	s_and_saveexec_b64 s[20:21], vcc
	s_cbranch_execz .LBB0_2230
	v_mov_b32_e32 v40, v209
	v_sub_f32_e32 v40, v40, v48
	v_mul_f32_e32 v56, 0x3fb8aa3b, v40
	v_fma_f32 v57, v40, s97, -v56
	v_rndne_f32_e32 v58, v56
	v_fmac_f32_e32 v57, 0x32a5705f, v40
	v_sub_f32_e32 v56, v56, v58
	v_add_f32_e32 v56, v56, v57
	v_cvt_i32_f32_e32 v58, v58
	v_exp_f32_e32 v56, v56
	v_cmp_ngt_f32_e32 vcc, s24, v40
	v_ldexp_f32 v56, v56, v58
	s_nop 0
	v_cndmask_b32_e32 v56, 0, v56, vcc
	v_cmp_nlt_f32_e32 vcc, s25, v40
	s_nop 1
	v_cndmask_b32_e32 v40, v188, v56, vcc
	v_mul_f32_e32 v40, v41, v40
.LBB0_2230:
	s_or_b64 exec, exec, s[20:21]
	v_add_u32_e32 v41, 18, v55
	v_cmp_le_u32_e32 vcc, v41, v103
	s_and_saveexec_b64 s[20:21], vcc
	s_cbranch_execz .LBB0_2232
	v_mov_b32_e32 v39, v210
	v_sub_f32_e32 v39, v39, v48
	v_mul_f32_e32 v41, 0x3fb8aa3b, v39
	v_fma_f32 v56, v39, s97, -v41
	v_rndne_f32_e32 v57, v41
	v_fmac_f32_e32 v56, 0x32a5705f, v39
	v_sub_f32_e32 v41, v41, v57
	v_add_f32_e32 v41, v41, v56
	v_cvt_i32_f32_e32 v57, v57
	v_exp_f32_e32 v41, v41
	v_cmp_ngt_f32_e32 vcc, s24, v39
	v_ldexp_f32 v41, v41, v57
	s_nop 0
	v_cndmask_b32_e32 v41, 0, v41, vcc
	v_cmp_nlt_f32_e32 vcc, s25, v39
	s_nop 1
	v_cndmask_b32_e32 v39, v188, v41, vcc
	v_mul_f32_e32 v39, v42, v39
.LBB0_2232:
	s_or_b64 exec, exec, s[20:21]
	v_add_u32_e32 v41, 19, v55
	v_cmp_le_u32_e32 vcc, v41, v103
	v_mov_b32_e32 v41, 0
	v_mov_b32_e32 v42, 0
	s_and_saveexec_b64 s[20:21], vcc
	s_cbranch_execz .LBB0_2234
	v_mov_b32_e32 v42, v211
	v_sub_f32_e32 v42, v42, v48
	v_mul_f32_e32 v56, 0x3fb8aa3b, v42
	v_fma_f32 v57, v42, s97, -v56
	v_rndne_f32_e32 v58, v56
	v_fmac_f32_e32 v57, 0x32a5705f, v42
	v_sub_f32_e32 v56, v56, v58
	v_add_f32_e32 v56, v56, v57
	v_cvt_i32_f32_e32 v58, v58
	v_exp_f32_e32 v56, v56
	v_cmp_ngt_f32_e32 vcc, s24, v42
	v_ldexp_f32 v56, v56, v58
	s_nop 0
	v_cndmask_b32_e32 v56, 0, v56, vcc
	v_cmp_nlt_f32_e32 vcc, s25, v42
	s_nop 1
	v_cndmask_b32_e32 v42, v188, v56, vcc
	v_mul_f32_e32 v42, v43, v42
.LBB0_2234:
	s_or_b64 exec, exec, s[20:21]
	v_add_u32_e32 v43, 24, v55
	v_cmp_le_u32_e32 vcc, v43, v103
	s_and_saveexec_b64 s[20:21], vcc
	s_cbranch_execz .LBB0_2236
	v_mov_b32_e32 v41, v212
	v_sub_f32_e32 v41, v41, v48
	v_mul_f32_e32 v43, 0x3fb8aa3b, v41
	v_fma_f32 v56, v41, s97, -v43
	v_rndne_f32_e32 v57, v43
	v_fmac_f32_e32 v56, 0x32a5705f, v41
	v_sub_f32_e32 v43, v43, v57
	v_add_f32_e32 v43, v43, v56
	v_cvt_i32_f32_e32 v57, v57
	v_exp_f32_e32 v43, v43
	v_cmp_ngt_f32_e32 vcc, s24, v41
	v_ldexp_f32 v43, v43, v57
	s_nop 0
	v_cndmask_b32_e32 v43, 0, v43, vcc
	v_cmp_nlt_f32_e32 vcc, s25, v41
	s_nop 1
	v_cndmask_b32_e32 v41, v188, v43, vcc
	v_mul_f32_e32 v41, v44, v41
.LBB0_2236:
	s_or_b64 exec, exec, s[20:21]
	v_add_u32_e32 v43, 25, v55
	v_cmp_le_u32_e32 vcc, v43, v103
	v_mov_b32_e32 v44, 0
	v_mov_b32_e32 v56, 0
	s_and_saveexec_b64 s[20:21], vcc
	s_cbranch_execz .LBB0_2238
	v_mov_b32_e32 v43, v213
	v_sub_f32_e32 v43, v43, v48
	v_mul_f32_e32 v56, 0x3fb8aa3b, v43
	v_fma_f32 v57, v43, s97, -v56
	v_rndne_f32_e32 v58, v56
	v_fmac_f32_e32 v57, 0x32a5705f, v43
	v_sub_f32_e32 v56, v56, v58
	v_add_f32_e32 v56, v56, v57
	v_cvt_i32_f32_e32 v58, v58
	v_exp_f32_e32 v56, v56
	v_cmp_ngt_f32_e32 vcc, s24, v43
	v_ldexp_f32 v56, v56, v58
	s_nop 0
	v_cndmask_b32_e32 v56, 0, v56, vcc
	v_cmp_nlt_f32_e32 vcc, s25, v43
	s_nop 1
	v_cndmask_b32_e32 v43, v188, v56, vcc
	v_mul_f32_e32 v56, v45, v43
.LBB0_2238:
	s_or_b64 exec, exec, s[20:21]
	v_add_u32_e32 v43, 26, v55
	v_cmp_le_u32_e32 vcc, v43, v103
	s_and_saveexec_b64 s[20:21], vcc
	s_cbranch_execz .LBB0_2240
	v_mov_b32_e32 v43, v214
	v_sub_f32_e32 v43, v43, v48
	v_mul_f32_e32 v44, 0x3fb8aa3b, v43
	v_fma_f32 v45, v43, s97, -v44
	v_rndne_f32_e32 v57, v44
	v_fmac_f32_e32 v45, 0x32a5705f, v43
	v_sub_f32_e32 v44, v44, v57
	v_add_f32_e32 v44, v44, v45
	v_cvt_i32_f32_e32 v57, v57
	v_exp_f32_e32 v44, v44
	v_cmp_ngt_f32_e32 vcc, s24, v43
	v_ldexp_f32 v44, v44, v57
	s_nop 0
	v_cndmask_b32_e32 v44, 0, v44, vcc
	v_cmp_nlt_f32_e32 vcc, s25, v43
	s_nop 1
	v_cndmask_b32_e32 v43, v188, v44, vcc
	v_mul_f32_e32 v44, v46, v43
.LBB0_2240:
	s_or_b64 exec, exec, s[20:21]
	v_add_u32_e32 v43, 27, v55
	v_cmp_le_u32_e32 vcc, v43, v103
	v_mov_b32_e32 v43, 0
	s_and_saveexec_b64 s[20:21], vcc
	s_cbranch_execz .LBB0_2209
	v_mov_b32_e32 v43, v215
	v_sub_f32_e32 v43, v43, v48
	v_mul_f32_e32 v45, 0x3fb8aa3b, v43
	v_fma_f32 v46, v43, s97, -v45
	v_rndne_f32_e32 v54, v45
	v_fmac_f32_e32 v46, 0x32a5705f, v43
	v_sub_f32_e32 v45, v45, v54
	v_add_f32_e32 v45, v45, v46
	v_cvt_i32_f32_e32 v54, v54
	v_exp_f32_e32 v45, v45
	v_cmp_ngt_f32_e32 vcc, s24, v43
	v_ldexp_f32 v45, v45, v54
	s_nop 0
	v_cndmask_b32_e32 v45, 0, v45, vcc
	v_cmp_nlt_f32_e32 vcc, s25, v43
	s_nop 1
	v_cndmask_b32_e32 v43, v188, v45, vcc
	v_mul_f32_e32 v43, v47, v43
	s_branch .LBB0_2209

.LBB0_4946:
	v_add_u32_e32 v60, v49, v104
	ds_read_b128 v[32:35], v60
	ds_read_b128 v[36:39], v105
	ds_read_b128 v[218:221], v60 offset:32
	ds_read_b128 v[222:225], v105 offset:32
	ds_read_b128 v[226:229], v60 offset:64
	ds_read_b128 v[230:233], v105 offset:64
	ds_read_b128 v[234:237], v60 offset:96
	ds_read_b128 v[238:241], v105 offset:96
	s_waitcnt lgkmcnt(6)
	v_mfma_f32_32x32x16_bf16 v[32:47], v[32:35], v[36:39], 0
	ds_read_b128 v[242:245], v60 offset:128
	ds_read_b128 v[246:249], v105 offset:128
	s_waitcnt lgkmcnt(6)
	v_mfma_f32_32x32x16_bf16 v[32:47], v[218:221], v[222:225], v[32:47]
	ds_read_b128 v[218:221], v60 offset:160
	ds_read_b128 v[222:225], v105 offset:160
	s_waitcnt lgkmcnt(6)
	v_mfma_f32_32x32x16_bf16 v[32:47], v[226:229], v[230:233], v[32:47]
	ds_read_b128 v[226:229], v60 offset:192
	ds_read_b128 v[230:233], v105 offset:192
	s_waitcnt lgkmcnt(6)
	v_mfma_f32_32x32x16_bf16 v[32:47], v[234:237], v[238:241], v[32:47]
	ds_read_b128 v[234:237], v60 offset:224
	ds_read_b128 v[238:241], v105 offset:224
	s_waitcnt lgkmcnt(6)
	v_mfma_f32_32x32x16_bf16 v[32:47], v[242:245], v[246:249], v[32:47]
	s_waitcnt lgkmcnt(4)
	v_mfma_f32_32x32x16_bf16 v[32:47], v[218:221], v[222:225], v[32:47]
	s_waitcnt lgkmcnt(2)
	v_mfma_f32_32x32x16_bf16 v[32:47], v[226:229], v[230:233], v[32:47]
	s_waitcnt lgkmcnt(0)
	v_mfma_f32_32x32x16_bf16 v[32:47], v[234:237], v[238:241], v[32:47]
	v_add_u32_e32 v55, s9, v107
	v_cmp_le_u32_e32 vcc, v55, v103
	v_add_u32_e32 v54, s8, v104
	v_add_u32_e32 v216, 0x22600, v54
	ds_read_b32 v200, v216
	ds_read_b32 v201, v216 offset:4
	ds_read_b32 v202, v216 offset:8
	ds_read_b32 v203, v216 offset:12
	ds_read_b32 v204, v216 offset:32
	ds_read_b32 v205, v216 offset:36
	ds_read_b32 v206, v216 offset:40
	ds_read_b32 v207, v216 offset:44
	ds_read_b32 v208, v216 offset:64
	ds_read_b32 v209, v216 offset:68
	ds_read_b32 v210, v216 offset:72
	ds_read_b32 v211, v216 offset:76
	s_waitcnt lgkmcnt(8)
	ds_read_b32 v212, v216 offset:96
	ds_read_b32 v213, v216 offset:100
	ds_read_b32 v214, v216 offset:104
	ds_read_b32 v215, v216 offset:108
	s_waitcnt lgkmcnt(0)
	v_mov_b32_e32 v52, 0
	s_and_saveexec_b64 s[6:7], vcc
	s_cbranch_execz .LBB0_4948
	v_mov_b32_e32 v52, v200
	v_sub_f32_e32 v52, v52, v48
	v_mul_f32_e32 v53, 0x3fb8aa3b, v52
	v_fma_f32 v56, v52, s13, -v53
	v_rndne_f32_e32 v57, v53
	v_fmac_f32_e32 v56, 0x32a5705f, v52
	v_sub_f32_e32 v53, v53, v57
	v_add_f32_e32 v53, v53, v56
	v_cvt_i32_f32_e32 v57, v57
	v_exp_f32_e32 v53, v53
	v_cmp_ngt_f32_e32 vcc, s14, v52
	v_ldexp_f32 v53, v53, v57
	s_nop 0
	v_cndmask_b32_e32 v53, 0, v53, vcc
	v_cmp_nlt_f32_e32 vcc, s15, v52
	s_nop 1
	v_cndmask_b32_e32 v52, v188, v53, vcc
	v_mul_f32_e32 v52, v32, v52
.LBB0_4948:
	s_or_b64 exec, exec, s[6:7]
	v_cmp_lt_u32_e32 vcc, v55, v103
	s_nop 3
	v_mov_b32_e32 v32, 0
	v_mov_b32_e32 v53, 0
	s_and_saveexec_b64 s[6:7], vcc
	s_cbranch_execz .LBB0_4950
	v_mov_b32_e32 v53, v201
	v_sub_f32_e32 v53, v53, v48
	v_mul_f32_e32 v56, 0x3fb8aa3b, v53
	v_fma_f32 v57, v53, s13, -v56
	v_rndne_f32_e32 v58, v56
	v_fmac_f32_e32 v57, 0x32a5705f, v53
	v_sub_f32_e32 v56, v56, v58
	v_add_f32_e32 v56, v56, v57
	v_cvt_i32_f32_e32 v58, v58
	v_exp_f32_e32 v56, v56
	v_cmp_ngt_f32_e32 vcc, s14, v53
	v_ldexp_f32 v56, v56, v58
	s_nop 0
	v_cndmask_b32_e32 v56, 0, v56, vcc
	v_cmp_nlt_f32_e32 vcc, s15, v53
	s_nop 1
	v_cndmask_b32_e32 v53, v188, v56, vcc
	v_mul_f32_e32 v53, v33, v53
.LBB0_4950:
	s_or_b64 exec, exec, s[6:7]
	v_add_u32_e32 v33, 2, v55
	v_cmp_le_u32_e32 vcc, v33, v103
	s_and_saveexec_b64 s[6:7], vcc
	s_cbranch_execz .LBB0_4952
	v_mov_b32_e32 v32, v202
	v_sub_f32_e32 v32, v32, v48
	v_mul_f32_e32 v33, 0x3fb8aa3b, v32
	v_fma_f32 v56, v32, s13, -v33
	v_rndne_f32_e32 v57, v33
	v_fmac_f32_e32 v56, 0x32a5705f, v32
	v_sub_f32_e32 v33, v33, v57
	v_add_f32_e32 v33, v33, v56
	v_cvt_i32_f32_e32 v57, v57
	v_exp_f32_e32 v33, v33
	v_cmp_ngt_f32_e32 vcc, s14, v32
	v_ldexp_f32 v33, v33, v57
	s_nop 0
	v_cndmask_b32_e32 v33, 0, v33, vcc
	v_cmp_nlt_f32_e32 vcc, s15, v32
	s_nop 1
	v_cndmask_b32_e32 v32, v188, v33, vcc
	v_mul_f32_e32 v32, v34, v32
.LBB0_4952:
	s_or_b64 exec, exec, s[6:7]
	v_add_u32_e32 v33, 3, v55
	v_cmp_le_u32_e32 vcc, v33, v103
	v_mov_b32_e32 v33, 0
	v_mov_b32_e32 v34, 0
	s_and_saveexec_b64 s[6:7], vcc
	s_cbranch_execz .LBB0_4954
	v_mov_b32_e32 v34, v203
	v_sub_f32_e32 v34, v34, v48
	v_mul_f32_e32 v56, 0x3fb8aa3b, v34
	v_fma_f32 v57, v34, s13, -v56
	v_rndne_f32_e32 v58, v56
	v_fmac_f32_e32 v57, 0x32a5705f, v34
	v_sub_f32_e32 v56, v56, v58
	v_add_f32_e32 v56, v56, v57
	v_cvt_i32_f32_e32 v58, v58
	v_exp_f32_e32 v56, v56
	v_cmp_ngt_f32_e32 vcc, s14, v34
	v_ldexp_f32 v56, v56, v58
	s_nop 0
	v_cndmask_b32_e32 v56, 0, v56, vcc
	v_cmp_nlt_f32_e32 vcc, s15, v34
	s_nop 1
	v_cndmask_b32_e32 v34, v188, v56, vcc
	v_mul_f32_e32 v34, v35, v34
.LBB0_4954:
	s_or_b64 exec, exec, s[6:7]
	v_add_u32_e32 v35, 8, v55
	v_cmp_le_u32_e32 vcc, v35, v103
	s_and_saveexec_b64 s[6:7], vcc
	s_cbranch_execz .LBB0_4956
	v_mov_b32_e32 v33, v204
	v_sub_f32_e32 v33, v33, v48
	v_mul_f32_e32 v35, 0x3fb8aa3b, v33
	v_fma_f32 v56, v33, s13, -v35
	v_rndne_f32_e32 v57, v35
	v_fmac_f32_e32 v56, 0x32a5705f, v33
	v_sub_f32_e32 v35, v35, v57
	v_add_f32_e32 v35, v35, v56
	v_cvt_i32_f32_e32 v57, v57
	v_exp_f32_e32 v35, v35
	v_cmp_ngt_f32_e32 vcc, s14, v33
	v_ldexp_f32 v35, v35, v57
	s_nop 0
	v_cndmask_b32_e32 v35, 0, v35, vcc
	v_cmp_nlt_f32_e32 vcc, s15, v33
	s_nop 1
	v_cndmask_b32_e32 v33, v188, v35, vcc
	v_mul_f32_e32 v33, v36, v33
.LBB0_4956:
	s_or_b64 exec, exec, s[6:7]
	v_add_u32_e32 v35, 9, v55
	v_cmp_le_u32_e32 vcc, v35, v103
	v_mov_b32_e32 v35, 0
	v_mov_b32_e32 v36, 0
	s_and_saveexec_b64 s[6:7], vcc
	s_cbranch_execz .LBB0_4958
	v_mov_b32_e32 v36, v205
	v_sub_f32_e32 v36, v36, v48
	v_mul_f32_e32 v56, 0x3fb8aa3b, v36
	v_fma_f32 v57, v36, s13, -v56
	v_rndne_f32_e32 v58, v56
	v_fmac_f32_e32 v57, 0x32a5705f, v36
	v_sub_f32_e32 v56, v56, v58
	v_add_f32_e32 v56, v56, v57
	v_cvt_i32_f32_e32 v58, v58
	v_exp_f32_e32 v56, v56
	v_cmp_ngt_f32_e32 vcc, s14, v36
	v_ldexp_f32 v56, v56, v58
	s_nop 0
	v_cndmask_b32_e32 v56, 0, v56, vcc
	v_cmp_nlt_f32_e32 vcc, s15, v36
	s_nop 1
	v_cndmask_b32_e32 v36, v188, v56, vcc
	v_mul_f32_e32 v36, v37, v36
.LBB0_4958:
	s_or_b64 exec, exec, s[6:7]
	v_add_u32_e32 v37, 10, v55
	v_cmp_le_u32_e32 vcc, v37, v103
	s_and_saveexec_b64 s[6:7], vcc
	s_cbranch_execz .LBB0_4960
	v_mov_b32_e32 v35, v206
	v_sub_f32_e32 v35, v35, v48
	v_mul_f32_e32 v37, 0x3fb8aa3b, v35
	v_fma_f32 v56, v35, s13, -v37
	v_rndne_f32_e32 v57, v37
	v_fmac_f32_e32 v56, 0x32a5705f, v35
	v_sub_f32_e32 v37, v37, v57
	v_add_f32_e32 v37, v37, v56
	v_cvt_i32_f32_e32 v57, v57
	v_exp_f32_e32 v37, v37
	v_cmp_ngt_f32_e32 vcc, s14, v35
	v_ldexp_f32 v37, v37, v57
	s_nop 0
	v_cndmask_b32_e32 v37, 0, v37, vcc
	v_cmp_nlt_f32_e32 vcc, s15, v35
	s_nop 1
	v_cndmask_b32_e32 v35, v188, v37, vcc
	v_mul_f32_e32 v35, v38, v35
.LBB0_4960:
	s_or_b64 exec, exec, s[6:7]
	v_add_u32_e32 v37, 11, v55
	v_cmp_le_u32_e32 vcc, v37, v103
	v_mov_b32_e32 v37, 0
	v_mov_b32_e32 v38, 0
	s_and_saveexec_b64 s[6:7], vcc
	s_cbranch_execz .LBB0_4962
	v_mov_b32_e32 v38, v207
	v_sub_f32_e32 v38, v38, v48
	v_mul_f32_e32 v56, 0x3fb8aa3b, v38
	v_fma_f32 v57, v38, s13, -v56
	v_rndne_f32_e32 v58, v56
	v_fmac_f32_e32 v57, 0x32a5705f, v38
	v_sub_f32_e32 v56, v56, v58
	v_add_f32_e32 v56, v56, v57
	v_cvt_i32_f32_e32 v58, v58
	v_exp_f32_e32 v56, v56
	v_cmp_ngt_f32_e32 vcc, s14, v38
	v_ldexp_f32 v56, v56, v58
	s_nop 0
	v_cndmask_b32_e32 v56, 0, v56, vcc
	v_cmp_nlt_f32_e32 vcc, s15, v38
	s_nop 1
	v_cndmask_b32_e32 v38, v188, v56, vcc
	v_mul_f32_e32 v38, v39, v38
.LBB0_4962:
	s_or_b64 exec, exec, s[6:7]
	v_add_u32_e32 v39, 16, v55
	v_cmp_le_u32_e32 vcc, v39, v103
	s_and_saveexec_b64 s[6:7], vcc
	s_cbranch_execz .LBB0_4964
	v_mov_b32_e32 v37, v208
	v_sub_f32_e32 v37, v37, v48
	v_mul_f32_e32 v39, 0x3fb8aa3b, v37
	v_fma_f32 v56, v37, s13, -v39
	v_rndne_f32_e32 v57, v39
	v_fmac_f32_e32 v56, 0x32a5705f, v37
	v_sub_f32_e32 v39, v39, v57
	v_add_f32_e32 v39, v39, v56
	v_cvt_i32_f32_e32 v57, v57
	v_exp_f32_e32 v39, v39
	v_cmp_ngt_f32_e32 vcc, s14, v37
	v_ldexp_f32 v39, v39, v57
	s_nop 0
	v_cndmask_b32_e32 v39, 0, v39, vcc
	v_cmp_nlt_f32_e32 vcc, s15, v37
	s_nop 1
	v_cndmask_b32_e32 v37, v188, v39, vcc
	v_mul_f32_e32 v37, v40, v37
.LBB0_4964:
	s_or_b64 exec, exec, s[6:7]
	v_add_u32_e32 v39, 17, v55
	v_cmp_le_u32_e32 vcc, v39, v103
	v_mov_b32_e32 v39, 0
	v_mov_b32_e32 v40, 0
	s_and_saveexec_b64 s[6:7], vcc
	s_cbranch_execz .LBB0_4966
	v_mov_b32_e32 v40, v209
	v_sub_f32_e32 v40, v40, v48
	v_mul_f32_e32 v56, 0x3fb8aa3b, v40
	v_fma_f32 v57, v40, s13, -v56
	v_rndne_f32_e32 v58, v56
	v_fmac_f32_e32 v57, 0x32a5705f, v40
	v_sub_f32_e32 v56, v56, v58
	v_add_f32_e32 v56, v56, v57
	v_cvt_i32_f32_e32 v58, v58
	v_exp_f32_e32 v56, v56
	v_cmp_ngt_f32_e32 vcc, s14, v40
	v_ldexp_f32 v56, v56, v58
	s_nop 0
	v_cndmask_b32_e32 v56, 0, v56, vcc
	v_cmp_nlt_f32_e32 vcc, s15, v40
	s_nop 1
	v_cndmask_b32_e32 v40, v188, v56, vcc
	v_mul_f32_e32 v40, v41, v40
.LBB0_4966:
	s_or_b64 exec, exec, s[6:7]
	v_add_u32_e32 v41, 18, v55
	v_cmp_le_u32_e32 vcc, v41, v103
	s_and_saveexec_b64 s[6:7], vcc
	s_cbranch_execz .LBB0_4968
	v_mov_b32_e32 v39, v210
	v_sub_f32_e32 v39, v39, v48
	v_mul_f32_e32 v41, 0x3fb8aa3b, v39
	v_fma_f32 v56, v39, s13, -v41
	v_rndne_f32_e32 v57, v41
	v_fmac_f32_e32 v56, 0x32a5705f, v39
	v_sub_f32_e32 v41, v41, v57
	v_add_f32_e32 v41, v41, v56
	v_cvt_i32_f32_e32 v57, v57
	v_exp_f32_e32 v41, v41
	v_cmp_ngt_f32_e32 vcc, s14, v39
	v_ldexp_f32 v41, v41, v57
	s_nop 0
	v_cndmask_b32_e32 v41, 0, v41, vcc
	v_cmp_nlt_f32_e32 vcc, s15, v39
	s_nop 1
	v_cndmask_b32_e32 v39, v188, v41, vcc
	v_mul_f32_e32 v39, v42, v39
.LBB0_4968:
	s_or_b64 exec, exec, s[6:7]
	v_add_u32_e32 v41, 19, v55
	v_cmp_le_u32_e32 vcc, v41, v103
	v_mov_b32_e32 v41, 0
	v_mov_b32_e32 v42, 0
	s_and_saveexec_b64 s[6:7], vcc
	s_cbranch_execz .LBB0_4970
	v_mov_b32_e32 v42, v211
	v_sub_f32_e32 v42, v42, v48
	v_mul_f32_e32 v56, 0x3fb8aa3b, v42
	v_fma_f32 v57, v42, s13, -v56
	v_rndne_f32_e32 v58, v56
	v_fmac_f32_e32 v57, 0x32a5705f, v42
	v_sub_f32_e32 v56, v56, v58
	v_add_f32_e32 v56, v56, v57
	v_cvt_i32_f32_e32 v58, v58
	v_exp_f32_e32 v56, v56
	v_cmp_ngt_f32_e32 vcc, s14, v42
	v_ldexp_f32 v56, v56, v58
	s_nop 0
	v_cndmask_b32_e32 v56, 0, v56, vcc
	v_cmp_nlt_f32_e32 vcc, s15, v42
	s_nop 1
	v_cndmask_b32_e32 v42, v188, v56, vcc
	v_mul_f32_e32 v42, v43, v42
.LBB0_4970:
	s_or_b64 exec, exec, s[6:7]
	v_add_u32_e32 v43, 24, v55
	v_cmp_le_u32_e32 vcc, v43, v103
	s_and_saveexec_b64 s[6:7], vcc
	s_cbranch_execz .LBB0_4972
	v_mov_b32_e32 v41, v212
	v_sub_f32_e32 v41, v41, v48
	v_mul_f32_e32 v43, 0x3fb8aa3b, v41
	v_fma_f32 v56, v41, s13, -v43
	v_rndne_f32_e32 v57, v43
	v_fmac_f32_e32 v56, 0x32a5705f, v41
	v_sub_f32_e32 v43, v43, v57
	v_add_f32_e32 v43, v43, v56
	v_cvt_i32_f32_e32 v57, v57
	v_exp_f32_e32 v43, v43
	v_cmp_ngt_f32_e32 vcc, s14, v41
	v_ldexp_f32 v43, v43, v57
	s_nop 0
	v_cndmask_b32_e32 v43, 0, v43, vcc
	v_cmp_nlt_f32_e32 vcc, s15, v41
	s_nop 1
	v_cndmask_b32_e32 v41, v188, v43, vcc
	v_mul_f32_e32 v41, v44, v41
.LBB0_4972:
	s_or_b64 exec, exec, s[6:7]
	v_add_u32_e32 v43, 25, v55
	v_cmp_le_u32_e32 vcc, v43, v103
	v_mov_b32_e32 v44, 0
	v_mov_b32_e32 v56, 0
	s_and_saveexec_b64 s[6:7], vcc
	s_cbranch_execz .LBB0_4974
	v_mov_b32_e32 v43, v213
	v_sub_f32_e32 v43, v43, v48
	v_mul_f32_e32 v56, 0x3fb8aa3b, v43
	v_fma_f32 v57, v43, s13, -v56
	v_rndne_f32_e32 v58, v56
	v_fmac_f32_e32 v57, 0x32a5705f, v43
	v_sub_f32_e32 v56, v56, v58
	v_add_f32_e32 v56, v56, v57
	v_cvt_i32_f32_e32 v58, v58
	v_exp_f32_e32 v56, v56
	v_cmp_ngt_f32_e32 vcc, s14, v43
	v_ldexp_f32 v56, v56, v58
	s_nop 0
	v_cndmask_b32_e32 v56, 0, v56, vcc
	v_cmp_nlt_f32_e32 vcc, s15, v43
	s_nop 1
	v_cndmask_b32_e32 v43, v188, v56, vcc
	v_mul_f32_e32 v56, v45, v43
.LBB0_4974:
	s_or_b64 exec, exec, s[6:7]
	v_add_u32_e32 v43, 26, v55
	v_cmp_le_u32_e32 vcc, v43, v103
	s_and_saveexec_b64 s[6:7], vcc
	s_cbranch_execz .LBB0_4976
	v_mov_b32_e32 v43, v214
	v_sub_f32_e32 v43, v43, v48
	v_mul_f32_e32 v44, 0x3fb8aa3b, v43
	v_fma_f32 v45, v43, s13, -v44
	v_rndne_f32_e32 v57, v44
	v_fmac_f32_e32 v45, 0x32a5705f, v43
	v_sub_f32_e32 v44, v44, v57
	v_add_f32_e32 v44, v44, v45
	v_cvt_i32_f32_e32 v57, v57
	v_exp_f32_e32 v44, v44
	v_cmp_ngt_f32_e32 vcc, s14, v43
	v_ldexp_f32 v44, v44, v57
	s_nop 0
	v_cndmask_b32_e32 v44, 0, v44, vcc
	v_cmp_nlt_f32_e32 vcc, s15, v43
	s_nop 1
	v_cndmask_b32_e32 v43, v188, v44, vcc
	v_mul_f32_e32 v44, v46, v43
.LBB0_4976:
	s_or_b64 exec, exec, s[6:7]
	v_add_u32_e32 v43, 27, v55
	v_cmp_le_u32_e32 vcc, v43, v103
	v_mov_b32_e32 v43, 0
	s_and_saveexec_b64 s[6:7], vcc
	s_cbranch_execz .LBB0_4945
	v_mov_b32_e32 v43, v215
	v_sub_f32_e32 v43, v43, v48
	v_mul_f32_e32 v45, 0x3fb8aa3b, v43
	v_fma_f32 v46, v43, s13, -v45
	v_rndne_f32_e32 v54, v45
	v_fmac_f32_e32 v46, 0x32a5705f, v43
	v_sub_f32_e32 v45, v45, v54
	v_add_f32_e32 v45, v45, v46
	v_cvt_i32_f32_e32 v54, v54
	v_exp_f32_e32 v45, v45
	v_cmp_ngt_f32_e32 vcc, s14, v43
	v_ldexp_f32 v45, v45, v54
	s_nop 0
	v_cndmask_b32_e32 v45, 0, v45, vcc
	v_cmp_nlt_f32_e32 vcc, s15, v43
	s_nop 1
	v_cndmask_b32_e32 v43, v188, v45, vcc
	v_mul_f32_e32 v43, v47, v43
	s_branch .LBB0_4945
